# FoX loop back-edge rotation (doc 7.11): loop-carried v_mov pair hoisted into the body, single conditional back branch
# baseline (speedup 1.0000x reference)
; __device__ __forceinline__ float ex2(float x) { return __builtin_amdgcn_exp2f(x); }
; template <bool FOX> ...
;     ...
; #pragma unroll
;     for (int qt = 0; qt < 2; ++qt) {
;       float mx = fmaxf(fmaxf(st[qt][0], st[qt][1]), fmaxf(st[qt][2], st[qt][3]));
; #pragma unroll
;       for (int r = 4; r < 16; r += 4) mx = fmaxf(fmaxf(mx, st[qt][r]), fmaxf(fmaxf(st[qt][r + 1], st[qt][r + 2]), st[qt][r + 3]));
;       mx = xmax32(mx);
;       const float mnew = fmaxf(mrun[qt], mx);
;       const float alpha = ex2(mrun[qt] - mnew);
;       mrun[qt] = mnew;
;       float ps0 = 0.f, ps1 = 0.f;
; #pragma unroll
;       for (int r = 0; r < 16; r += 2) {
;         float p0 = ex2(st[qt][r] - mnew), p1 = ex2(st[qt][r + 1] - mnew);
;         ps0 += p0; ps1 += p1;
;         st[qt][r] = p0; st[qt][r + 1] = p1;
;       }
;       lrun[qt] = lrun[qt] * alpha + (ps0 + ps1);
; #pragma unroll
;       for (int dt = 0; dt < 2; ++dt) o[dt][qt] = o[dt][qt] * alpha;
.LBB0_512:
	s_nop 7
	v_max_f32_e32 v182, v98, v99
	v_max3_f32 v182, v96, v97, v182
	v_max3_f32 v194, v101, v102, v103
	v_max3_f32 v182, v182, v100, v194
	v_max3_f32 v194, v105, v106, v107
	v_max3_f32 v182, v182, v104, v194
	v_max3_f32 v194, v109, v110, v111
	v_max3_f32 v182, v182, v108, v194
	v_mov_b32_e32 v194, v182
	s_nop 1
	v_permlane32_swap_b32_e32 v182, v194
	v_max3_f32 v182, v185, v182, v194
	v_pk_add_f32 v[96:97], v[96:97], v[182:183] op_sel_hi:[1,0] neg_lo:[0,1] neg_hi:[0,1]
	v_pk_add_f32 v[98:99], v[98:99], v[182:183] op_sel_hi:[1,0] neg_lo:[0,1] neg_hi:[0,1]
	v_pk_add_f32 v[100:101], v[100:101], v[182:183] op_sel_hi:[1,0] neg_lo:[0,1] neg_hi:[0,1]
	v_pk_add_f32 v[102:103], v[102:103], v[182:183] op_sel_hi:[1,0] neg_lo:[0,1] neg_hi:[0,1]
	v_exp_f32_e32 v194, v96
	v_exp_f32_e32 v196, v97
	v_exp_f32_e32 v198, v98
	v_exp_f32_e32 v200, v99
	v_exp_f32_e32 v202, v100
	v_exp_f32_e32 v204, v101
	v_exp_f32_e32 v206, v102
	v_exp_f32_e32 v208, v103
	v_pk_add_f32 v[96:97], v[104:105], v[182:183] op_sel_hi:[1,0] neg_lo:[0,1] neg_hi:[0,1]
	v_pk_add_f32 v[106:107], v[106:107], v[182:183] op_sel_hi:[1,0] neg_lo:[0,1] neg_hi:[0,1]
	v_pk_add_f32 v[108:109], v[108:109], v[182:183] op_sel_hi:[1,0] neg_lo:[0,1] neg_hi:[0,1]
	v_pk_add_f32 v[110:111], v[110:111], v[182:183] op_sel_hi:[1,0] neg_lo:[0,1] neg_hi:[0,1]
	v_max_f32_e32 v104, v82, v83
	v_max3_f32 v104, v80, v81, v104
	v_max3_f32 v105, v85, v86, v87
	v_max3_f32 v104, v104, v84, v105
	v_max3_f32 v105, v89, v90, v91
	v_max3_f32 v104, v104, v88, v105
	v_max3_f32 v105, v93, v94, v95
	v_max3_f32 v104, v104, v92, v105
	v_mov_b32_e32 v105, v104
	s_nop 1
	v_permlane32_swap_b32_e32 v104, v105
	v_max3_f32 v104, v113, v104, v105
	v_exp_f32_e32 v210, v96
	v_exp_f32_e32 v212, v97
	v_exp_f32_e32 v106, v106
	v_exp_f32_e32 v214, v107
	v_exp_f32_e32 v108, v108
	v_exp_f32_e32 v216, v109
	v_exp_f32_e32 v110, v110
	v_exp_f32_e32 v234, v111
	v_pk_add_f32 v[80:81], v[80:81], v[104:105] op_sel_hi:[1,0] neg_lo:[0,1] neg_hi:[0,1]
	v_pk_add_f32 v[82:83], v[82:83], v[104:105] op_sel_hi:[1,0] neg_lo:[0,1] neg_hi:[0,1]
	v_pk_add_f32 v[84:85], v[84:85], v[104:105] op_sel_hi:[1,0] neg_lo:[0,1] neg_hi:[0,1]
	v_pk_add_f32 v[86:87], v[86:87], v[104:105] op_sel_hi:[1,0] neg_lo:[0,1] neg_hi:[0,1]
	v_pk_add_f32 v[88:89], v[88:89], v[104:105] op_sel_hi:[1,0] neg_lo:[0,1] neg_hi:[0,1]
	v_pk_add_f32 v[90:91], v[90:91], v[104:105] op_sel_hi:[1,0] neg_lo:[0,1] neg_hi:[0,1]
	v_pk_add_f32 v[92:93], v[92:93], v[104:105] op_sel_hi:[1,0] neg_lo:[0,1] neg_hi:[0,1]
	v_pk_add_f32 v[94:95], v[94:95], v[104:105] op_sel_hi:[1,0] neg_lo:[0,1] neg_hi:[0,1]
	v_exp_f32_e32 v195, v80
	v_exp_f32_e32 v197, v81
	v_exp_f32_e32 v199, v82
	v_exp_f32_e32 v201, v83
	v_exp_f32_e32 v203, v84
	v_exp_f32_e32 v205, v85
	v_exp_f32_e32 v207, v86
	v_exp_f32_e32 v209, v87
	v_exp_f32_e32 v211, v88
	v_exp_f32_e32 v213, v89
	v_exp_f32_e32 v107, v90
	v_exp_f32_e32 v215, v91
	v_exp_f32_e32 v109, v92
	v_exp_f32_e32 v217, v93
	v_exp_f32_e32 v111, v94
	v_exp_f32_e32 v235, v95
	v_sub_f32_e32 v185, v185, v182
	v_pk_add_f32 v[80:81], v[194:195], 0 op_sel_hi:[1,0]
	v_pk_add_f32 v[82:83], v[196:197], 0 op_sel_hi:[1,0]
	v_exp_f32_e32 v236, v185
	v_mov_b32_e32 v185, v182
	v_pk_add_f32 v[80:81], v[198:199], v[80:81]
	v_pk_add_f32 v[82:83], v[200:201], v[82:83]
	v_pk_add_f32 v[80:81], v[202:203], v[80:81]
	v_pk_add_f32 v[82:83], v[204:205], v[82:83]
	v_pk_add_f32 v[80:81], v[206:207], v[80:81]
	v_pk_add_f32 v[82:83], v[208:209], v[82:83]
	v_sub_f32_e32 v105, v113, v104
	v_mov_b32_e32 v113, v104
	v_pk_add_f32 v[80:81], v[210:211], v[80:81]
	v_pk_add_f32 v[82:83], v[212:213], v[82:83]
	v_pk_mul_f32 v[62:63], v[62:63], v[236:237] op_sel_hi:[1,0]
	v_pk_mul_f32 v[60:61], v[60:61], v[236:237] op_sel_hi:[1,0]
	v_pk_mul_f32 v[58:59], v[58:59], v[236:237] op_sel_hi:[1,0]
	v_pk_mul_f32 v[56:57], v[56:57], v[236:237] op_sel_hi:[1,0]
	v_pk_mul_f32 v[54:55], v[54:55], v[236:237] op_sel_hi:[1,0]
	v_pk_mul_f32 v[52:53], v[52:53], v[236:237] op_sel_hi:[1,0]
	v_pk_mul_f32 v[50:51], v[50:51], v[236:237] op_sel_hi:[1,0]
	v_pk_mul_f32 v[48:49], v[48:49], v[236:237] op_sel_hi:[1,0]
	v_pk_mul_f32 v[46:47], v[46:47], v[236:237] op_sel_hi:[1,0]
	v_pk_mul_f32 v[44:45], v[44:45], v[236:237] op_sel_hi:[1,0]
	v_pk_mul_f32 v[42:43], v[42:43], v[236:237] op_sel_hi:[1,0]
	v_pk_mul_f32 v[40:41], v[40:41], v[236:237] op_sel_hi:[1,0]
	v_pk_mul_f32 v[38:39], v[38:39], v[236:237] op_sel_hi:[1,0]
	v_pk_mul_f32 v[36:37], v[36:37], v[236:237] op_sel_hi:[1,0]
	v_pk_mul_f32 v[34:35], v[34:35], v[236:237] op_sel_hi:[1,0]
	v_pk_mul_f32 v[32:33], v[32:33], v[236:237] op_sel_hi:[1,0]
	v_exp_f32_e32 v237, v105
	v_pk_add_f32 v[80:81], v[106:107], v[80:81]
	v_pk_add_f32 v[82:83], v[214:215], v[82:83]
	v_pk_add_f32 v[80:81], v[108:109], v[80:81]
	v_pk_add_f32 v[82:83], v[216:217], v[82:83]
	v_pk_add_f32 v[80:81], v[110:111], v[80:81]
	v_pk_add_f32 v[82:83], v[234:235], v[82:83]
	v_cvt_pk_bf16_f32 v100, v194, v196
	v_cvt_pk_bf16_f32 v101, v198, v200
	v_cvt_pk_bf16_f32 v102, v202, v204
	v_cvt_pk_bf16_f32 v103, v206, v208
	v_cvt_pk_bf16_f32 v84, v195, v197
	s_nop 0
	v_pk_add_f32 v[80:81], v[80:81], v[82:83]
	v_cvt_pk_bf16_f32 v85, v199, v201
	v_cvt_pk_bf16_f32 v86, v203, v205
	v_cvt_pk_bf16_f32 v87, v207, v209
	s_waitcnt vmcnt(3)
; template <bool FOX> ...
;     ...
;     kp += 2048;
;     vp += 2048;
;     cp += 32;
;     if (kt + 1 < kt1) {
;     ...
;       lrun[qt] = lrun[qt] * alpha + (ps0 + ps1);
; #pragma unroll
;       for (int dt = 0; dt < 2; ++dt) o[dt][qt] = o[dt][qt] * alpha;
; #pragma unroll
;       for (int ks = 0; ks < 2; ++ks) {
;         union { bf16x8 v; uint32_t w[4]; } u;
; #pragma unroll
;         for (int e = 0; e < 4; ++e) u.w[e] = pack2(st[qt][8 * ks + 2 * e], st[qt][8 * ks + 2 * e + 1]);
;         bp[qt][ks] = u.v;
;       }
;     }
; #pragma unroll
;     for (int dt = 0; dt < 2; ++dt)
; #pragma unroll
;       for (int qt = 0; qt < 2; ++qt)
; #pragma unroll
;         for (int ks = 0; ks < 2; ++ks) o[dt][qt] = mfma32(av[dt][ks], bp[qt][ks], o[dt][qt]);
	v_mfma_f32_32x32x16_bf16 v[48:63], v[174:177], v[100:103], v[48:63]
	v_fma_f32 v188, v188, v236, v80
	v_fma_f32 v189, v189, v237, v81
	v_mov_b32_e32 v80, v237
	v_mul_f32_e64 v30, v30, v80
	v_mul_f32_e64 v31, v31, v80
	v_pk_mul_f32 v[28:29], v[28:29], v[80:81] op_sel_hi:[1,0]
	v_pk_mul_f32 v[26:27], v[26:27], v[80:81] op_sel_hi:[1,0]
	v_pk_mul_f32 v[24:25], v[24:25], v[80:81] op_sel_hi:[1,0]
	v_pk_mul_f32 v[22:23], v[22:23], v[80:81] op_sel_hi:[1,0]
	v_pk_mul_f32 v[20:21], v[20:21], v[80:81] op_sel_hi:[1,0]
	v_pk_mul_f32 v[18:19], v[18:19], v[80:81] op_sel_hi:[1,0]
	v_pk_mul_f32 v[16:17], v[16:17], v[80:81] op_sel_hi:[1,0]
	v_pk_mul_f32 v[14:15], v[14:15], v[80:81] op_sel_hi:[1,0]
	v_pk_mul_f32 v[12:13], v[12:13], v[80:81] op_sel_hi:[1,0]
	v_pk_mul_f32 v[10:11], v[10:11], v[80:81] op_sel_hi:[1,0]
	v_pk_mul_f32 v[8:9], v[8:9], v[80:81] op_sel_hi:[1,0]
	v_pk_mul_f32 v[6:7], v[6:7], v[80:81] op_sel_hi:[1,0]
	v_pk_mul_f32 v[4:5], v[4:5], v[80:81] op_sel_hi:[1,0]
	v_pk_mul_f32 v[2:3], v[2:3], v[80:81] op_sel_hi:[1,0]
	v_pk_mul_f32 v[0:1], v[0:1], v[80:81] op_sel_hi:[1,0]
	v_mfma_f32_32x32x16_bf16 v[16:31], v[174:177], v[84:87], v[16:31]
	v_cvt_pk_bf16_f32 v96, v210, v212
	v_cvt_pk_bf16_f32 v97, v106, v214
	v_cvt_pk_bf16_f32 v98, v108, v216
	v_cvt_pk_bf16_f32 v99, v110, v234
	v_cvt_pk_bf16_f32 v80, v211, v213
	v_cvt_pk_bf16_f32 v81, v107, v215
	v_cvt_pk_bf16_f32 v82, v109, v217
	s_waitcnt vmcnt(1)
	v_mfma_f32_32x32x16_bf16 v[32:47], v[166:169], v[100:103], v[32:47]
	v_cvt_pk_bf16_f32 v83, v111, v235
	s_add_i32 s10, s10, 32
	v_lshl_add_u64 v[190:191], v[190:191], 0, s[68:69]
	v_lshl_add_u64 v[192:193], v[192:193], 0, s[86:87]
	s_cmp_eq_u32 s8, s9
	v_mfma_f32_32x32x16_bf16 v[0:15], v[166:169], v[84:87], v[0:15]
	v_mfma_f32_32x32x16_bf16 v[48:63], v[170:173], v[96:99], v[48:63]
	v_mfma_f32_32x32x16_bf16 v[16:31], v[170:173], v[80:83], v[16:31]
	s_waitcnt vmcnt(0)
	v_mfma_f32_32x32x16_bf16 v[32:47], v[162:165], v[96:99], v[32:47]
	v_mfma_f32_32x32x16_bf16 v[0:15], v[162:165], v[80:83], v[0:15]
	s_cbranch_scc0 .LBB0_508
	s_branch .LBB0_505
